# diff attention tile A: shorter wave-uniform rescale test on the common path (first-tile and need cases branch out; common path goes straight to the tile-B classification)
# speedup vs baseline: 1.0060x; 1.0018x over previous
; template <bool HAS_QK, bool HAS_PV> ...
;     ...
;         const float rm = rowmax32(s0, s1);
;         need = first || __any(rm > 8.f);
;         if (need) { const float dl = first ? rm : fmaxf(rm, 0.f); mrun += dl; f = first ? 1.f : __builtin_amdgcn_exp2f(-dl);
; #pragma unroll
;             for (int r = 0; r < 16; ++r) { s0[r] -= dl; s1[r] -= dl; } }
.LBB0_209:
	v_max_f32_e32 v0, v128, v80
	v_max_f32_e32 v4, v129, v81
	v_max3_f32 v0, v0, v130, v82
	v_max3_f32 v4, v4, v131, v83
	v_max3_f32 v0, v0, v132, v84
	v_max3_f32 v4, v4, v133, v85
	v_max3_f32 v0, v0, v134, v86
	v_max3_f32 v4, v4, v135, v87
	v_max3_f32 v0, v0, v136, v88
	v_max3_f32 v4, v4, v137, v89
	v_max3_f32 v0, v0, v138, v90
	v_max3_f32 v4, v4, v139, v91
	v_max3_f32 v0, v0, v140, v92
	v_max3_f32 v4, v4, v141, v93
	v_max3_f32 v0, v0, v142, v94
	v_max3_f32 v4, v4, v143, v95
	v_max_f32_e32 v0, v0, v4
	s_cmp_eq_u32 s29, 0
	s_cbranch_scc1 .Ldiff_first_a
	v_cmp_lt_f32_e32 vcc, s86, v0
	s_cbranch_vccnz .Ldiff_need_a
	v_mov_b32_e32 v0, 1.0
	s_branch .LBB0_214
.Ldiff_first_a:
	s_mov_b64 s[4:5], 0
	s_branch .Ldiff_combine_a
.Ldiff_need_a:
	s_mov_b64 s[4:5], -1
